# GEMM unit headers: the 128 accumulator registers zeroed with 64 v_mov_b64 instead of 128 v_mov_b32
# speedup vs baseline: 1.0090x; 1.0090x over previous
;     DI size_t a_row(int pm) const { return (size_t)pm * 256; }
; template <class Epi, class Sched, bool ALIGN_EPI>
; DI void gemm_phase(LAS unsigned char* lds, const Gemm g, const Sched& S, const Epi& E) {
;     ...
;         const bool has_next = S.next(ui + 1, nxt);
;         const char* nA = has_next ? (const char*)g.A + S.a_row(nxt.pm) * rowb + (size_t)nxt.kt0 * kstep : cA; const char* nB = has_next ? (const char*)g.Bt + (size_t)nxt.pn * 2 * hstep + (size_t)nxt.kt0 * kstep : cB;
;     ...
; #pragma unroll
;         for (int a = 0; a < 2; ++a)
; #pragma unroll
;             for (int b = 0; b < 2; ++b)
; #pragma unroll
;                 for (int m = 0; m < 4; ++m)
; #pragma unroll
;                     for (int n = 0; n < 2; ++n) acc[a][b][m][n] = (f32x4){0.f, 0.f, 0.f, 0.f};
;         cur = nxt; cA = nA; cB = nB; ++ui;
.LBB0_103:
	s_ashr_i32 s31, s30, 31
	s_lshl_b64 s[34:35], s[30:31], 19
	s_add_u32 s34, s27, s34
	s_addc_u32 s35, s33, s35
	s_and_b64 s[42:43], s[4:5], exec
	s_cselect_b32 s7, s35, s1
	s_cselect_b32 s11, s34, s0
	s_ashr_i32 s29, s28, 31
	s_lshl_b64 s[42:43], s[28:29], 19
	s_add_u32 s42, s61, s42
	s_addc_u32 s43, s62, s43
	s_and_b64 s[44:45], s[4:5], exec
	s_cselect_b32 s18, s43, s9
	s_cselect_b32 s29, s42, s8
	s_add_u32 s0, s0, 0x40080
	s_addc_u32 s1, s1, 0
	s_add_u32 s31, s8, 0x100
	v_mov_b64_e32 v[0:1], 0
	s_addc_u32 s46, s9, 0
	s_mov_b32 s47, -2
	v_mov_b64_e32 v[2:3], 0
	v_mov_b64_e32 v[4:5], 0
	v_mov_b64_e32 v[6:7], 0
	v_mov_b64_e32 v[16:17], 0
	v_mov_b64_e32 v[18:19], 0
	v_mov_b64_e32 v[20:21], 0
	s_waitcnt lgkmcnt(0)
	v_mov_b64_e32 v[22:23], 0
	v_mov_b64_e32 v[32:33], 0
	v_mov_b64_e32 v[34:35], 0
	v_mov_b64_e32 v[36:37], 0
	v_mov_b64_e32 v[38:39], 0
	v_mov_b64_e32 v[64:65], 0
	v_mov_b64_e32 v[66:67], 0
	v_mov_b64_e32 v[68:69], 0
	v_mov_b64_e32 v[70:71], 0
	v_mov_b64_e32 v[8:9], 0
	v_mov_b64_e32 v[10:11], 0
	v_mov_b64_e32 v[12:13], 0
	v_mov_b64_e32 v[14:15], 0
	v_mov_b64_e32 v[24:25], 0
	v_mov_b64_e32 v[26:27], 0
	v_mov_b64_e32 v[28:29], 0
	v_mov_b64_e32 v[30:31], 0
	v_mov_b64_e32 v[40:41], 0
	v_mov_b64_e32 v[42:43], 0
	v_mov_b64_e32 v[44:45], 0
	v_mov_b64_e32 v[46:47], 0
	v_mov_b64_e32 v[72:73], 0
	v_mov_b64_e32 v[74:75], 0
	v_mov_b64_e32 v[76:77], 0
	v_mov_b64_e32 v[78:79], 0
	v_mov_b64_e32 v[80:81], 0
	v_mov_b64_e32 v[82:83], 0
	v_mov_b64_e32 v[84:85], 0
	v_mov_b64_e32 v[86:87], 0
	v_mov_b64_e32 v[96:97], 0
	v_mov_b64_e32 v[98:99], 0
	v_mov_b64_e32 v[100:101], 0
	v_mov_b64_e32 v[102:103], 0
	v_mov_b64_e32 v[112:113], 0
	v_mov_b64_e32 v[114:115], 0
	v_mov_b64_e32 v[116:117], 0
	v_mov_b64_e32 v[118:119], 0
	v_mov_b64_e32 v[128:129], 0
	v_mov_b64_e32 v[130:131], 0
	v_mov_b64_e32 v[132:133], 0
	v_mov_b64_e32 v[134:135], 0
	v_mov_b64_e32 v[88:89], 0
	v_mov_b64_e32 v[90:91], 0
	v_mov_b64_e32 v[92:93], 0
	v_mov_b64_e32 v[94:95], 0
	v_mov_b64_e32 v[104:105], 0
	v_mov_b64_e32 v[106:107], 0
	v_mov_b64_e32 v[108:109], 0
	v_mov_b64_e32 v[110:111], 0
	v_mov_b64_e32 v[120:121], 0
	v_mov_b64_e32 v[122:123], 0
	v_mov_b64_e32 v[124:125], 0
	v_mov_b64_e32 v[126:127], 0
	v_mov_b64_e32 v[136:137], 0
	v_mov_b64_e32 v[138:139], 0
	v_mov_b64_e32 v[140:141], 0
	v_mov_b64_e32 v[142:143], 0

; template <class Epi, class Sched, bool ALIGN_EPI>
; DI void gemm_phase(LAS unsigned char* lds, const Gemm g, const Sched& S, const Epi& E) {
;     ...
; #pragma unroll
;         for (int a = 0; a < 2; ++a)
; #pragma unroll
;             for (int b = 0; b < 2; ++b)
; #pragma unroll
;                 for (int m = 0; m < 4; ++m)
; #pragma unroll
;                     for (int n = 0; n < 2; ++n) acc[a][b][m][n] = (f32x4){0.f, 0.f, 0.f, 0.f};
;         cur = nxt; cA = nA; cB = nB; ++ui;
.LBB0_790:
	s_add_u32 s0, s0, 0xb0080
	s_addc_u32 s1, s1, 0
	s_add_u32 s35, s4, 0x100
	v_mov_b64_e32 v[0:1], 0
	s_addc_u32 s36, s5, 0
	s_mov_b32 s37, -2
	v_mov_b64_e32 v[2:3], 0
	v_mov_b64_e32 v[4:5], 0
	v_mov_b64_e32 v[6:7], 0
	v_mov_b64_e32 v[12:13], 0
	v_mov_b64_e32 v[14:15], 0
	v_mov_b64_e32 v[20:21], 0
	v_mov_b64_e32 v[22:23], 0
	v_mov_b64_e32 v[28:29], 0
	v_mov_b64_e32 v[30:31], 0
	v_mov_b64_e32 v[36:37], 0
	v_mov_b64_e32 v[38:39], 0
	v_mov_b64_e32 v[44:45], 0
	v_mov_b64_e32 v[46:47], 0
	s_waitcnt vmcnt(0)
	v_mov_b64_e32 v[52:53], 0
	v_mov_b64_e32 v[54:55], 0
	v_mov_b64_e32 v[8:9], 0
	v_mov_b64_e32 v[10:11], 0
	v_mov_b64_e32 v[16:17], 0
	v_mov_b64_e32 v[18:19], 0
	v_mov_b64_e32 v[24:25], 0
	v_mov_b64_e32 v[26:27], 0
	v_mov_b64_e32 v[32:33], 0
	v_mov_b64_e32 v[34:35], 0
	v_mov_b64_e32 v[40:41], 0
	v_mov_b64_e32 v[42:43], 0
	v_mov_b64_e32 v[48:49], 0
	v_mov_b64_e32 v[50:51], 0
	v_mov_b64_e32 v[56:57], 0
	v_mov_b64_e32 v[58:59], 0
	v_mov_b64_e32 v[60:61], 0
	v_mov_b64_e32 v[62:63], 0
	v_mov_b64_e32 v[64:65], 0
	v_mov_b64_e32 v[66:67], 0
	v_mov_b64_e32 v[68:69], 0
	v_mov_b64_e32 v[70:71], 0
	v_mov_b64_e32 v[76:77], 0
	v_mov_b64_e32 v[78:79], 0
	v_mov_b64_e32 v[84:85], 0
	v_mov_b64_e32 v[86:87], 0
	v_mov_b64_e32 v[92:93], 0
	v_mov_b64_e32 v[94:95], 0
	v_mov_b64_e32 v[100:101], 0
	v_mov_b64_e32 v[102:103], 0
	v_mov_b64_e32 v[112:113], 0
	v_mov_b64_e32 v[114:115], 0
	v_mov_b64_e32 v[116:117], 0
	v_mov_b64_e32 v[118:119], 0
	v_mov_b64_e32 v[72:73], 0
	v_mov_b64_e32 v[74:75], 0
	v_mov_b64_e32 v[80:81], 0
	v_mov_b64_e32 v[82:83], 0
	v_mov_b64_e32 v[88:89], 0
	v_mov_b64_e32 v[90:91], 0
	v_mov_b64_e32 v[96:97], 0
	v_mov_b64_e32 v[98:99], 0
	v_mov_b64_e32 v[104:105], 0
	v_mov_b64_e32 v[106:107], 0
	v_mov_b64_e32 v[108:109], 0
	v_mov_b64_e32 v[110:111], 0
	v_mov_b64_e32 v[120:121], 0
	v_mov_b64_e32 v[122:123], 0
	v_mov_b64_e32 v[124:125], 0
	v_mov_b64_e32 v[126:127], 0

; template <class Epi, class Sched, bool ALIGN_EPI>
; DI void gemm_phase(LAS unsigned char* lds, const Gemm g, const Sched& S, const Epi& E) {
;     ...
; #pragma unroll
;         for (int a = 0; a < 2; ++a)
; #pragma unroll
;             for (int b = 0; b < 2; ++b)
; #pragma unroll
;                 for (int m = 0; m < 4; ++m)
; #pragma unroll
;                     for (int n = 0; n < 2; ++n) acc[a][b][m][n] = (f32x4){0.f, 0.f, 0.f, 0.f};
;         cur = nxt; cA = nA; cB = nB; ++ui;
.LBB0_825:
	s_ashr_i32 s23, s22, 31
	s_lshl_b64 s[26:27], s[22:23], 19
	v_readlane_b32 s23, v253, 12
	s_add_u32 s26, s23, s26
	v_readlane_b32 s23, v253, 13
	s_addc_u32 s27, s23, s27
	s_and_b64 s[34:35], s[34:35], exec
	s_cselect_b32 s23, s27, s31
	s_cselect_b32 s29, s26, s30
	s_add_u32 s0, s0, 0x40080
	s_addc_u32 s1, s1, 0
	s_add_u32 s43, s30, 0x100
	v_mov_b64_e32 v[0:1], 0
	s_addc_u32 s44, s31, 0
	s_mov_b32 s45, -2
	v_mov_b64_e32 v[2:3], 0
	v_mov_b64_e32 v[80:81], 0
	v_mov_b64_e32 v[82:83], 0
	v_mov_b64_e32 v[8:9], 0
	v_mov_b64_e32 v[10:11], 0
	v_mov_b64_e32 v[88:89], 0
	v_mov_b64_e32 v[90:91], 0
	v_mov_b64_e32 v[16:17], 0
	v_mov_b64_e32 v[18:19], 0
	v_mov_b64_e32 v[96:97], 0
	v_mov_b64_e32 v[98:99], 0
	v_mov_b64_e32 v[24:25], 0
	v_mov_b64_e32 v[26:27], 0
	v_mov_b64_e32 v[104:105], 0
	v_mov_b64_e32 v[106:107], 0
	v_mov_b64_e32 v[4:5], 0
	v_mov_b64_e32 v[6:7], 0
	v_mov_b64_e32 v[84:85], 0
	v_mov_b64_e32 v[86:87], 0
	v_mov_b64_e32 v[12:13], 0
	v_mov_b64_e32 v[14:15], 0
	v_mov_b64_e32 v[92:93], 0
	v_mov_b64_e32 v[94:95], 0
	v_mov_b64_e32 v[20:21], 0
	v_mov_b64_e32 v[22:23], 0
	v_mov_b64_e32 v[100:101], 0
	v_mov_b64_e32 v[102:103], 0
	v_mov_b64_e32 v[28:29], 0
	v_mov_b64_e32 v[30:31], 0
	v_mov_b64_e32 v[108:109], 0
	v_mov_b64_e32 v[110:111], 0
	v_mov_b64_e32 v[32:33], 0
	v_mov_b64_e32 v[34:35], 0
	v_mov_b64_e32 v[112:113], 0
	v_mov_b64_e32 v[114:115], 0
	v_mov_b64_e32 v[40:41], 0
	v_mov_b64_e32 v[42:43], 0
	v_mov_b64_e32 v[120:121], 0
	v_mov_b64_e32 v[122:123], 0
	v_mov_b64_e32 v[64:65], 0
	v_mov_b64_e32 v[66:67], 0
	v_mov_b64_e32 v[144:145], 0
	v_mov_b64_e32 v[146:147], 0
	v_mov_b64_e32 v[72:73], 0
	v_mov_b64_e32 v[74:75], 0
	v_mov_b64_e32 v[152:153], 0
	v_mov_b64_e32 v[154:155], 0
	v_mov_b64_e32 v[36:37], 0
	v_mov_b64_e32 v[38:39], 0
	v_mov_b64_e32 v[116:117], 0
	v_mov_b64_e32 v[118:119], 0
	s_waitcnt vmcnt(0)
	v_mov_b64_e32 v[60:61], 0
	v_mov_b64_e32 v[62:63], 0
	v_mov_b64_e32 v[140:141], 0
	v_mov_b64_e32 v[142:143], 0
	v_mov_b64_e32 v[68:69], 0
	v_mov_b64_e32 v[70:71], 0
	v_mov_b64_e32 v[148:149], 0
	v_mov_b64_e32 v[150:151], 0
	v_mov_b64_e32 v[76:77], 0
	v_mov_b64_e32 v[78:79], 0
	v_mov_b64_e32 v[156:157], 0
	v_mov_b64_e32 v[158:159], 0

;     DI bool next(int i, Unit& u) const {
;         if (i >= cnt) return false;
;         const int idx = s + i * stride;
;         if (KIND == 4) { const int g = idx / 176, w = idx - 176 * g, gsz = (73 - 8 * g) < 8 ? (73 - 8 * g) : 8;
;             u.pm = 8 * g + w % gsz; u.pn = w / gsz; u.kt0 = 0; u.nkt = 16; }
;         else { u.pm = idx >> 2; u.pn = idx & 3; u.kt0 = 0; u.nkt = KIND == 5 ? 44 : 16; }
; template <class Epi, class Sched, bool ALIGN_EPI>
; DI void gemm_phase(LAS unsigned char* lds, const Gemm g, const Sched& S, const Epi& E) {
;     ...
; #pragma unroll
;         for (int a = 0; a < 2; ++a)
; #pragma unroll
;             for (int b = 0; b < 2; ++b)
; #pragma unroll
;                 for (int m = 0; m < 4; ++m)
; #pragma unroll
;                     for (int n = 0; n < 2; ++n) acc[a][b][m][n] = (f32x4){0.f, 0.f, 0.f, 0.f};
;         cur = nxt; cA = nA; cB = nB; ++ui;
.LBB0_956:
	s_mov_b32 s30, s29
	s_add_i32 s29, s29, 1
	s_cmp_lt_u32 s29, s91
	s_mul_i32 s5, s29, s90
	s_cselect_b64 s[18:19], -1, 0
	s_add_i32 s5, s5, s89
	s_ashr_i32 s5, s5, 2
	s_mov_b64 s[16:17], s[6:7]
	s_and_b64 s[6:7], s[18:19], exec
	s_mov_b32 s31, s4
	s_cselect_b32 s4, s5, s4
	s_mov_b32 s33, s14
	s_cselect_b32 s14, s21, s14
	s_ashr_i32 s5, s4, 31
	s_lshl_b64 s[6:7], s[4:5], 19
	s_mov_b64 s[0:1], s[8:9]
	s_add_u32 s8, s52, s6
	s_addc_u32 s9, s53, s7
	s_and_b64 s[6:7], s[18:19], exec
	s_cselect_b32 s5, s9, s1
	s_cselect_b32 s34, s8, s0
	s_ashr_i32 s15, s14, 31
	s_lshl_b64 s[6:7], s[14:15], 19
	s_add_u32 s6, s60, s6
	s_addc_u32 s7, s82, s7
	s_and_b64 s[18:19], s[18:19], exec
	s_cselect_b32 s15, s7, s17
	s_cselect_b32 s35, s6, s16
	s_add_u32 s0, s0, 0x40080
	s_addc_u32 s1, s1, 0
	s_add_u32 s36, s16, 0x100
	v_mov_b64_e32 v[0:1], 0
	s_addc_u32 s37, s17, 0
	s_mov_b32 s42, -2
	s_waitcnt lgkmcnt(0)
	v_mov_b64_e32 v[2:3], 0
	v_mov_b64_e32 v[4:5], 0
	v_mov_b64_e32 v[6:7], 0
	v_mov_b64_e32 v[16:17], 0
	v_mov_b64_e32 v[18:19], 0
	v_mov_b64_e32 v[20:21], 0
	v_mov_b64_e32 v[22:23], 0
	v_mov_b64_e32 v[32:33], 0
	v_mov_b64_e32 v[34:35], 0
	v_mov_b64_e32 v[36:37], 0
	v_mov_b64_e32 v[38:39], 0
	s_waitcnt vmcnt(0)
	v_mov_b64_e32 v[48:49], 0
	v_mov_b64_e32 v[50:51], 0
	v_mov_b64_e32 v[52:53], 0
	v_mov_b64_e32 v[54:55], 0
	v_mov_b64_e32 v[8:9], 0
	v_mov_b64_e32 v[10:11], 0
	v_mov_b64_e32 v[12:13], 0
	v_mov_b64_e32 v[14:15], 0
	v_mov_b64_e32 v[24:25], 0
	v_mov_b64_e32 v[26:27], 0
	v_mov_b64_e32 v[28:29], 0
	v_mov_b64_e32 v[30:31], 0
	v_mov_b64_e32 v[40:41], 0
	v_mov_b64_e32 v[42:43], 0
	v_mov_b64_e32 v[44:45], 0
	v_mov_b64_e32 v[46:47], 0
	v_mov_b64_e32 v[56:57], 0
	v_mov_b64_e32 v[58:59], 0
	v_mov_b64_e32 v[60:61], 0
	v_mov_b64_e32 v[62:63], 0
	v_mov_b64_e32 v[64:65], 0
	v_mov_b64_e32 v[66:67], 0
	v_mov_b64_e32 v[68:69], 0
	v_mov_b64_e32 v[70:71], 0
	v_mov_b64_e32 v[80:81], 0
	v_mov_b64_e32 v[82:83], 0
	v_mov_b64_e32 v[84:85], 0
	v_mov_b64_e32 v[86:87], 0
	v_mov_b64_e32 v[96:97], 0
	v_mov_b64_e32 v[98:99], 0
	v_mov_b64_e32 v[100:101], 0
	v_mov_b64_e32 v[102:103], 0
	v_mov_b64_e32 v[112:113], 0
	v_mov_b64_e32 v[114:115], 0
	v_mov_b64_e32 v[116:117], 0
	v_mov_b64_e32 v[118:119], 0
	v_mov_b64_e32 v[72:73], 0
	v_mov_b64_e32 v[74:75], 0
	v_mov_b64_e32 v[76:77], 0
	v_mov_b64_e32 v[78:79], 0
	v_mov_b64_e32 v[88:89], 0
	v_mov_b64_e32 v[90:91], 0
	v_mov_b64_e32 v[92:93], 0
	v_mov_b64_e32 v[94:95], 0
	v_mov_b64_e32 v[104:105], 0
	v_mov_b64_e32 v[106:107], 0
	v_mov_b64_e32 v[108:109], 0
	v_mov_b64_e32 v[110:111], 0
	v_mov_b64_e32 v[120:121], 0
	v_mov_b64_e32 v[122:123], 0
	v_mov_b64_e32 v[124:125], 0
	v_mov_b64_e32 v[126:127], 0
